# GEMM K-loops: loop-invariant LDS fragment-read address adds hoisted out of the load-segment heads into 4 spare VGPRs
# speedup vs baseline: 1.0087x; 1.0053x over previous
.Lgprio0:
	v_add_u32_e32 v236, 0x10000, v175
	v_add_u32_e32 v237, 0x14000, v175
	v_add_u32_e32 v238, 0x18000, v175
	v_add_u32_e32 v239, 0x1c000, v175
.LBB0_169:
	s_add_u32 s42, s40, 0xfff80080
	s_addc_u32 s43, s41, -1
	s_add_i32 s52, 0, 0x10000
	s_cmp_eq_u32 s51, 28
	s_cselect_b32 s45, s13, s43
	s_cselect_b32 s44, s47, s42
	s_cselect_b32 s43, s11, s50
	s_cselect_b32 s42, s48, s49
	s_add_i32 s54, 0, 0x14000
	ds_read_b128 v[130:133], v236
	ds_read_b128 v[134:137], v236 offset:1024
	ds_read_b128 v[138:141], v236 offset:2048
	ds_read_b128 v[142:145], v236 offset:3072
	ds_read_b128 v[170:173], v237
	ds_read_b128 v[184:187], v237 offset:1024
	ds_read_b128 v[188:191], v237 offset:2048
	ds_read_b128 v[192:195], v237 offset:3072
	s_add_i32 m0, s14, 0xc000
	ds_read_b128 v[196:199], v183
	ds_read_b128 v[200:203], v183 offset:1024
	ds_read_b128 v[210:213], v183 offset:2048
	ds_read_b128 v[214:217], v183 offset:3072
	ds_read_b128 v[218:221], v183 offset:4096
	ds_read_b128 v[222:225], v183 offset:5120
	ds_read_b128 v[226:229], v183 offset:6144
	ds_read_b128 v[230:233], v183 offset:7168
	global_load_lds_dwordx4 v166, s[40:41]
	s_add_i32 m0, s14, 0xe000
	s_nop 0
	global_load_lds_dwordx4 v168, s[40:41]
	s_waitcnt vmcnt(8) lgkmcnt(0)
	s_barrier
	v_mfma_f32_16x16x32_bf16 v[126:129], v[130:133], v[196:199], v[126:129]
	v_mfma_f32_16x16x32_bf16 v[122:125], v[138:141], v[196:199], v[122:125]
	v_mfma_f32_16x16x32_bf16 v[118:121], v[130:133], v[210:213], v[118:121]
	v_mfma_f32_16x16x32_bf16 v[110:113], v[138:141], v[210:213], v[110:113]
	v_mfma_f32_16x16x32_bf16 v[102:105], v[130:133], v[218:221], v[102:105]
	v_mfma_f32_16x16x32_bf16 v[94:97], v[138:141], v[218:221], v[94:97]
	v_mfma_f32_16x16x32_bf16 v[86:89], v[130:133], v[226:229], v[86:89]
	v_mfma_f32_16x16x32_bf16 v[78:81], v[138:141], v[226:229], v[78:81]
	v_mfma_f32_16x16x32_bf16 v[126:129], v[134:137], v[200:203], v[126:129]
	v_mfma_f32_16x16x32_bf16 v[122:125], v[142:145], v[200:203], v[122:125]
	v_mfma_f32_16x16x32_bf16 v[118:121], v[134:137], v[214:217], v[118:121]
	v_mfma_f32_16x16x32_bf16 v[110:113], v[142:145], v[214:217], v[110:113]
	v_mfma_f32_16x16x32_bf16 v[102:105], v[134:137], v[222:225], v[102:105]
	v_mfma_f32_16x16x32_bf16 v[94:97], v[142:145], v[222:225], v[94:97]
	v_mfma_f32_16x16x32_bf16 v[86:89], v[134:137], v[230:233], v[86:89]
	v_mfma_f32_16x16x32_bf16 v[78:81], v[142:145], v[230:233], v[78:81]
	v_mfma_f32_16x16x32_bf16 v[114:117], v[170:173], v[196:199], v[114:117]
	v_mfma_f32_16x16x32_bf16 v[106:109], v[188:191], v[196:199], v[106:109]
	v_mfma_f32_16x16x32_bf16 v[98:101], v[170:173], v[210:213], v[98:101]
	v_mfma_f32_16x16x32_bf16 v[90:93], v[188:191], v[210:213], v[90:93]
	v_mfma_f32_16x16x32_bf16 v[82:85], v[170:173], v[218:221], v[82:85]
	v_mfma_f32_16x16x32_bf16 v[74:77], v[188:191], v[218:221], v[74:77]
	v_mfma_f32_16x16x32_bf16 v[70:73], v[170:173], v[226:229], v[70:73]
	v_mfma_f32_16x16x32_bf16 v[66:69], v[188:191], v[226:229], v[66:69]
	v_mfma_f32_16x16x32_bf16 v[114:117], v[184:187], v[200:203], v[114:117]
	v_mfma_f32_16x16x32_bf16 v[106:109], v[192:195], v[200:203], v[106:109]
	v_mfma_f32_16x16x32_bf16 v[98:101], v[184:187], v[214:217], v[98:101]
	v_mfma_f32_16x16x32_bf16 v[90:93], v[192:195], v[214:217], v[90:93]
	v_mfma_f32_16x16x32_bf16 v[82:85], v[184:187], v[222:225], v[82:85]
	v_mfma_f32_16x16x32_bf16 v[74:77], v[192:195], v[222:225], v[74:77]
	v_mfma_f32_16x16x32_bf16 v[70:73], v[184:187], v[230:233], v[70:73]
	v_mfma_f32_16x16x32_bf16 v[66:69], v[192:195], v[230:233], v[66:69]
	s_barrier
	s_add_i32 s52, s52, s5
	v_lshl_add_u64 v[154:155], s[42:43], 0, v[162:163]
	s_mov_b32 m0, s52
	ds_read_b128 v[196:199], v183 offset:16384
	ds_read_b128 v[200:203], v183 offset:17408
	ds_read_b128 v[210:213], v183 offset:18432
	ds_read_b128 v[214:217], v183 offset:19456
	ds_read_b128 v[218:221], v183 offset:20480
	ds_read_b128 v[222:225], v183 offset:21504
	ds_read_b128 v[226:229], v183 offset:22528
	ds_read_b128 v[230:233], v183 offset:23552
	global_load_lds_dwordx4 v[154:155], off
	s_add_i32 m0, s52, 0x2000
	s_add_u32 s52, s42, 0x80000
	v_lshl_add_u64 v[156:157], s[42:43], 0, v[158:159]
	s_addc_u32 s53, s43, 0
	s_add_i32 s54, s54, s5
	global_load_lds_dwordx4 v[156:157], off
	s_mov_b32 m0, s54
	v_lshl_add_u64 v[180:181], s[44:45], 0, v[160:161]
	global_load_lds_dwordx4 v162, s[52:53]
	s_add_i32 m0, s54, 0x2000
	s_nop 0
	global_load_lds_dwordx4 v158, s[52:53]
	v_lshl_add_u64 v[176:177], s[44:45], 0, v[164:165]
	s_mov_b32 m0, s14
	s_nop 0
	global_load_lds_dwordx4 v[176:177], off
	s_mov_b32 m0, s15
	s_nop 0
	global_load_lds_dwordx4 v[180:181], off
	s_waitcnt vmcnt(8) lgkmcnt(0)
	s_barrier
	v_mfma_f32_16x16x32_bf16 v[62:65], v[130:133], v[196:199], v[62:65]
	v_mfma_f32_16x16x32_bf16 v[58:61], v[138:141], v[196:199], v[58:61]
	v_mfma_f32_16x16x32_bf16 v[54:57], v[130:133], v[210:213], v[54:57]
	v_mfma_f32_16x16x32_bf16 v[46:49], v[138:141], v[210:213], v[46:49]
	v_mfma_f32_16x16x32_bf16 v[38:41], v[130:133], v[218:221], v[38:41]
	v_mfma_f32_16x16x32_bf16 v[30:33], v[138:141], v[218:221], v[30:33]
	v_mfma_f32_16x16x32_bf16 v[22:25], v[130:133], v[226:229], v[22:25]
	v_mfma_f32_16x16x32_bf16 v[14:17], v[138:141], v[226:229], v[14:17]
	v_mfma_f32_16x16x32_bf16 v[62:65], v[134:137], v[200:203], v[62:65]
	v_mfma_f32_16x16x32_bf16 v[58:61], v[142:145], v[200:203], v[58:61]
	v_mfma_f32_16x16x32_bf16 v[54:57], v[134:137], v[214:217], v[54:57]
	v_mfma_f32_16x16x32_bf16 v[46:49], v[142:145], v[214:217], v[46:49]
	v_mfma_f32_16x16x32_bf16 v[38:41], v[134:137], v[222:225], v[38:41]
	v_mfma_f32_16x16x32_bf16 v[30:33], v[142:145], v[222:225], v[30:33]
	v_mfma_f32_16x16x32_bf16 v[22:25], v[134:137], v[230:233], v[22:25]
	v_mfma_f32_16x16x32_bf16 v[14:17], v[142:145], v[230:233], v[14:17]
	v_mfma_f32_16x16x32_bf16 v[50:53], v[170:173], v[196:199], v[50:53]
	v_mfma_f32_16x16x32_bf16 v[42:45], v[188:191], v[196:199], v[42:45]
	v_mfma_f32_16x16x32_bf16 v[34:37], v[170:173], v[210:213], v[34:37]
	v_mfma_f32_16x16x32_bf16 v[26:29], v[188:191], v[210:213], v[26:29]
	v_mfma_f32_16x16x32_bf16 v[18:21], v[170:173], v[218:221], v[18:21]
	v_mfma_f32_16x16x32_bf16 v[10:13], v[188:191], v[218:221], v[10:13]
	v_mfma_f32_16x16x32_bf16 v[6:9], v[170:173], v[226:229], v[6:9]
	v_mfma_f32_16x16x32_bf16 v[2:5], v[188:191], v[226:229], v[2:5]
	v_mfma_f32_16x16x32_bf16 v[50:53], v[184:187], v[200:203], v[50:53]
	v_mfma_f32_16x16x32_bf16 v[42:45], v[192:195], v[200:203], v[42:45]
	v_mfma_f32_16x16x32_bf16 v[34:37], v[184:187], v[214:217], v[34:37]
	v_mfma_f32_16x16x32_bf16 v[26:29], v[192:195], v[214:217], v[26:29]
	v_mfma_f32_16x16x32_bf16 v[18:21], v[184:187], v[222:225], v[18:21]
	v_mfma_f32_16x16x32_bf16 v[10:13], v[192:195], v[222:225], v[10:13]
	v_mfma_f32_16x16x32_bf16 v[6:9], v[184:187], v[230:233], v[6:9]
	v_mfma_f32_16x16x32_bf16 v[2:5], v[192:195], v[230:233], v[2:5]
	s_barrier
	s_add_i32 s52, 0, 0x18000
	s_add_i32 s53, 0, 0x1c000
	ds_read_b128 v[130:133], v238
	ds_read_b128 v[134:137], v238 offset:1024
	ds_read_b128 v[138:141], v238 offset:2048
	ds_read_b128 v[142:145], v238 offset:3072
	ds_read_b128 v[170:173], v239
	ds_read_b128 v[184:187], v239 offset:1024
	ds_read_b128 v[188:191], v239 offset:2048
	ds_read_b128 v[192:195], v239 offset:3072
	s_add_u32 s44, s44, 0x80000
	s_addc_u32 s45, s45, 0
	s_mov_b32 m0, s16
	ds_read_b128 v[196:199], v183 offset:32768
	ds_read_b128 v[200:203], v183 offset:33792
	ds_read_b128 v[210:213], v183 offset:34816
	ds_read_b128 v[214:217], v183 offset:35840
	ds_read_b128 v[218:221], v183 offset:36864
	ds_read_b128 v[222:225], v183 offset:37888
	ds_read_b128 v[226:229], v183 offset:38912
	ds_read_b128 v[230:233], v183 offset:39936
	global_load_lds_dwordx4 v164, s[44:45]
	s_mov_b32 m0, s18
	s_nop 0
	global_load_lds_dwordx4 v160, s[44:45]
	s_waitcnt vmcnt(8) lgkmcnt(0)
	s_barrier
	v_mfma_f32_16x16x32_bf16 v[126:129], v[130:133], v[196:199], v[126:129]
	v_mfma_f32_16x16x32_bf16 v[122:125], v[138:141], v[196:199], v[122:125]
	v_mfma_f32_16x16x32_bf16 v[118:121], v[130:133], v[210:213], v[118:121]
	v_mfma_f32_16x16x32_bf16 v[110:113], v[138:141], v[210:213], v[110:113]
	v_mfma_f32_16x16x32_bf16 v[102:105], v[130:133], v[218:221], v[102:105]
	v_mfma_f32_16x16x32_bf16 v[94:97], v[138:141], v[218:221], v[94:97]
	v_mfma_f32_16x16x32_bf16 v[86:89], v[130:133], v[226:229], v[86:89]
	v_mfma_f32_16x16x32_bf16 v[78:81], v[138:141], v[226:229], v[78:81]
	v_mfma_f32_16x16x32_bf16 v[126:129], v[134:137], v[200:203], v[126:129]
	v_mfma_f32_16x16x32_bf16 v[122:125], v[142:145], v[200:203], v[122:125]
	v_mfma_f32_16x16x32_bf16 v[118:121], v[134:137], v[214:217], v[118:121]
	v_mfma_f32_16x16x32_bf16 v[110:113], v[142:145], v[214:217], v[110:113]
	v_mfma_f32_16x16x32_bf16 v[102:105], v[134:137], v[222:225], v[102:105]
	v_mfma_f32_16x16x32_bf16 v[94:97], v[142:145], v[222:225], v[94:97]
	v_mfma_f32_16x16x32_bf16 v[86:89], v[134:137], v[230:233], v[86:89]
	v_mfma_f32_16x16x32_bf16 v[78:81], v[142:145], v[230:233], v[78:81]
	v_mfma_f32_16x16x32_bf16 v[114:117], v[170:173], v[196:199], v[114:117]
	v_mfma_f32_16x16x32_bf16 v[106:109], v[188:191], v[196:199], v[106:109]
	v_mfma_f32_16x16x32_bf16 v[98:101], v[170:173], v[210:213], v[98:101]
	v_mfma_f32_16x16x32_bf16 v[90:93], v[188:191], v[210:213], v[90:93]
	v_mfma_f32_16x16x32_bf16 v[82:85], v[170:173], v[218:221], v[82:85]
	v_mfma_f32_16x16x32_bf16 v[74:77], v[188:191], v[218:221], v[74:77]
	v_mfma_f32_16x16x32_bf16 v[70:73], v[170:173], v[226:229], v[70:73]
	v_mfma_f32_16x16x32_bf16 v[66:69], v[188:191], v[226:229], v[66:69]
	v_mfma_f32_16x16x32_bf16 v[114:117], v[184:187], v[200:203], v[114:117]
	v_mfma_f32_16x16x32_bf16 v[106:109], v[192:195], v[200:203], v[106:109]
	v_mfma_f32_16x16x32_bf16 v[98:101], v[184:187], v[214:217], v[98:101]
	v_mfma_f32_16x16x32_bf16 v[90:93], v[192:195], v[214:217], v[90:93]
	v_mfma_f32_16x16x32_bf16 v[82:85], v[184:187], v[222:225], v[82:85]
	v_mfma_f32_16x16x32_bf16 v[74:77], v[192:195], v[222:225], v[74:77]
	v_mfma_f32_16x16x32_bf16 v[70:73], v[184:187], v[230:233], v[70:73]
	v_mfma_f32_16x16x32_bf16 v[66:69], v[192:195], v[230:233], v[66:69]
	s_barrier
	s_add_i32 s44, s52, s5
	v_lshl_add_u64 v[154:155], v[154:155], 0, s[34:35]
	s_mov_b32 m0, s44
	ds_read_b128 v[196:199], v183 offset:49152
	ds_read_b128 v[200:203], v183 offset:50176
	ds_read_b128 v[210:213], v183 offset:51200
	ds_read_b128 v[214:217], v183 offset:52224
	ds_read_b128 v[218:221], v183 offset:53248
	ds_read_b128 v[222:225], v183 offset:54272
	ds_read_b128 v[226:229], v183 offset:55296
	ds_read_b128 v[230:233], v183 offset:56320
	global_load_lds_dwordx4 v[154:155], off
	s_add_i32 m0, s44, 0x2000
	s_add_u32 s42, s42, 0x80080
	v_lshl_add_u64 v[154:155], v[156:157], 0, s[34:35]
	s_addc_u32 s43, s43, 0
	s_add_i32 s44, s53, s5
	global_load_lds_dwordx4 v[154:155], off
	s_mov_b32 m0, s44
	s_nop 0
	global_load_lds_dwordx4 v162, s[42:43]
	s_add_i32 m0, s44, 0x2000
	s_nop 0
	global_load_lds_dwordx4 v158, s[42:43]
	v_lshl_add_u64 v[154:155], v[176:177], 0, s[34:35]
	s_mov_b32 m0, s19
	s_nop 0
	global_load_lds_dwordx4 v[154:155], off
	v_lshl_add_u64 v[154:155], v[180:181], 0, s[34:35]
	s_mov_b32 m0, s25
	s_nop 0
	global_load_lds_dwordx4 v[154:155], off
	s_waitcnt vmcnt(8) lgkmcnt(0)
	s_barrier
	v_mfma_f32_16x16x32_bf16 v[62:65], v[130:133], v[196:199], v[62:65]
	v_mfma_f32_16x16x32_bf16 v[58:61], v[138:141], v[196:199], v[58:61]
	v_mfma_f32_16x16x32_bf16 v[54:57], v[130:133], v[210:213], v[54:57]
	v_mfma_f32_16x16x32_bf16 v[46:49], v[138:141], v[210:213], v[46:49]
	v_mfma_f32_16x16x32_bf16 v[38:41], v[130:133], v[218:221], v[38:41]
	v_mfma_f32_16x16x32_bf16 v[30:33], v[138:141], v[218:221], v[30:33]
	v_mfma_f32_16x16x32_bf16 v[22:25], v[130:133], v[226:229], v[22:25]
	v_mfma_f32_16x16x32_bf16 v[14:17], v[138:141], v[226:229], v[14:17]
	v_mfma_f32_16x16x32_bf16 v[62:65], v[134:137], v[200:203], v[62:65]
	v_mfma_f32_16x16x32_bf16 v[58:61], v[142:145], v[200:203], v[58:61]
	v_mfma_f32_16x16x32_bf16 v[54:57], v[134:137], v[214:217], v[54:57]
	v_mfma_f32_16x16x32_bf16 v[46:49], v[142:145], v[214:217], v[46:49]
	v_mfma_f32_16x16x32_bf16 v[38:41], v[134:137], v[222:225], v[38:41]
	v_mfma_f32_16x16x32_bf16 v[30:33], v[142:145], v[222:225], v[30:33]
	v_mfma_f32_16x16x32_bf16 v[22:25], v[134:137], v[230:233], v[22:25]
	v_mfma_f32_16x16x32_bf16 v[14:17], v[142:145], v[230:233], v[14:17]
	v_mfma_f32_16x16x32_bf16 v[50:53], v[170:173], v[196:199], v[50:53]
	v_mfma_f32_16x16x32_bf16 v[42:45], v[188:191], v[196:199], v[42:45]
	v_mfma_f32_16x16x32_bf16 v[34:37], v[170:173], v[210:213], v[34:37]
	v_mfma_f32_16x16x32_bf16 v[26:29], v[188:191], v[210:213], v[26:29]
	v_mfma_f32_16x16x32_bf16 v[18:21], v[170:173], v[218:221], v[18:21]
	v_mfma_f32_16x16x32_bf16 v[10:13], v[188:191], v[218:221], v[10:13]
	v_mfma_f32_16x16x32_bf16 v[6:9], v[170:173], v[226:229], v[6:9]
	v_mfma_f32_16x16x32_bf16 v[2:5], v[188:191], v[226:229], v[2:5]
	v_mfma_f32_16x16x32_bf16 v[50:53], v[184:187], v[200:203], v[50:53]
	v_mfma_f32_16x16x32_bf16 v[42:45], v[192:195], v[200:203], v[42:45]
	v_mfma_f32_16x16x32_bf16 v[34:37], v[184:187], v[214:217], v[34:37]
	v_mfma_f32_16x16x32_bf16 v[26:29], v[192:195], v[214:217], v[26:29]
	v_mfma_f32_16x16x32_bf16 v[18:21], v[184:187], v[222:225], v[18:21]
	v_mfma_f32_16x16x32_bf16 v[10:13], v[192:195], v[222:225], v[10:13]
	v_mfma_f32_16x16x32_bf16 v[6:9], v[184:187], v[230:233], v[6:9]
	v_mfma_f32_16x16x32_bf16 v[2:5], v[192:195], v[230:233], v[2:5]
	s_barrier
	s_add_i32 s51, s51, 2
	s_add_u32 s40, s40, 0x100
	s_addc_u32 s41, s41, 0
	s_add_u32 s49, s49, 0x100
	s_addc_u32 s50, s50, 0
	s_cmp_gt_u32 s51, 29
	s_cbranch_scc0 .LBB0_169
	s_setprio 0
	s_and_b64 vcc, exec, s[8:9]
	s_cbranch_vccz .LBB0_172
	s_barrier

.Lgprio1:
	v_add_u32_e32 v236, 0x10000, v172
	v_add_u32_e32 v237, 0x14000, v172
	v_add_u32_e32 v238, 0x18000, v172
	v_add_u32_e32 v239, 0x1c000, v172
.LBB0_516:
	s_add_u32 s46, s44, 0xfff80080
	s_addc_u32 s47, s45, -1
	s_add_i32 s58, 0, 0x10000
	s_cmp_eq_u32 s57, 28
	s_cselect_b32 s49, s21, s47
	s_cselect_b32 s48, s50, s46
	s_cselect_b32 s47, s13, s56
	s_cselect_b32 s46, s51, s55
	s_add_i32 s60, 0, 0x14000
	ds_read_b128 v[82:85], v236
	ds_read_b128 v[86:89], v236 offset:1024
	ds_read_b128 v[98:101], v236 offset:2048
	ds_read_b128 v[102:105], v236 offset:3072
	ds_read_b128 v[154:157], v237
	ds_read_b128 v[168:171], v237 offset:1024
	ds_read_b128 v[176:179], v237 offset:2048
	ds_read_b128 v[180:183], v237 offset:3072
	s_add_i32 m0, s14, 0xc000
	ds_read_b128 v[184:187], v174
	ds_read_b128 v[188:191], v174 offset:1024
	ds_read_b128 v[192:195], v174 offset:2048
	ds_read_b128 v[196:199], v174 offset:3072
	ds_read_b128 v[200:203], v174 offset:4096
	ds_read_b128 v[210:213], v174 offset:5120
	ds_read_b128 v[214:217], v174 offset:6144
	ds_read_b128 v[218:221], v174 offset:7168
	global_load_lds_dwordx4 v164, s[44:45]
	s_add_i32 m0, s14, 0xe000
	s_nop 0
	global_load_lds_dwordx4 v166, s[44:45]
	s_waitcnt vmcnt(8) lgkmcnt(0)
	s_barrier
	v_mfma_f32_16x16x32_bf16 v[142:145], v[82:85], v[184:187], v[142:145]
	v_mfma_f32_16x16x32_bf16 v[138:141], v[98:101], v[184:187], v[138:141]
	v_mfma_f32_16x16x32_bf16 v[126:129], v[82:85], v[192:195], v[126:129]
	v_mfma_f32_16x16x32_bf16 v[122:125], v[98:101], v[192:195], v[122:125]
	v_mfma_f32_16x16x32_bf16 v[110:113], v[82:85], v[200:203], v[110:113]
	v_mfma_f32_16x16x32_bf16 v[106:109], v[98:101], v[200:203], v[106:109]
	v_mfma_f32_16x16x32_bf16 v[78:81], v[82:85], v[214:217], v[78:81]
	v_mfma_f32_16x16x32_bf16 v[74:77], v[98:101], v[214:217], v[74:77]
	v_mfma_f32_16x16x32_bf16 v[142:145], v[86:89], v[188:191], v[142:145]
	v_mfma_f32_16x16x32_bf16 v[138:141], v[102:105], v[188:191], v[138:141]
	v_mfma_f32_16x16x32_bf16 v[126:129], v[86:89], v[196:199], v[126:129]
	v_mfma_f32_16x16x32_bf16 v[122:125], v[102:105], v[196:199], v[122:125]
	v_mfma_f32_16x16x32_bf16 v[110:113], v[86:89], v[210:213], v[110:113]
	v_mfma_f32_16x16x32_bf16 v[106:109], v[102:105], v[210:213], v[106:109]
	v_mfma_f32_16x16x32_bf16 v[78:81], v[86:89], v[218:221], v[78:81]
	v_mfma_f32_16x16x32_bf16 v[74:77], v[102:105], v[218:221], v[74:77]
	v_mfma_f32_16x16x32_bf16 v[134:137], v[154:157], v[184:187], v[134:137]
	v_mfma_f32_16x16x32_bf16 v[130:133], v[176:179], v[184:187], v[130:133]
	v_mfma_f32_16x16x32_bf16 v[118:121], v[154:157], v[192:195], v[118:121]
	v_mfma_f32_16x16x32_bf16 v[114:117], v[176:179], v[192:195], v[114:117]
	v_mfma_f32_16x16x32_bf16 v[94:97], v[154:157], v[200:203], v[94:97]
	v_mfma_f32_16x16x32_bf16 v[90:93], v[176:179], v[200:203], v[90:93]
	v_mfma_f32_16x16x32_bf16 v[70:73], v[154:157], v[214:217], v[70:73]
	v_mfma_f32_16x16x32_bf16 v[66:69], v[176:179], v[214:217], v[66:69]
	v_mfma_f32_16x16x32_bf16 v[134:137], v[168:171], v[188:191], v[134:137]
	v_mfma_f32_16x16x32_bf16 v[130:133], v[180:183], v[188:191], v[130:133]
	v_mfma_f32_16x16x32_bf16 v[118:121], v[168:171], v[196:199], v[118:121]
	v_mfma_f32_16x16x32_bf16 v[114:117], v[180:183], v[196:199], v[114:117]
	v_mfma_f32_16x16x32_bf16 v[94:97], v[168:171], v[210:213], v[94:97]
	v_mfma_f32_16x16x32_bf16 v[90:93], v[180:183], v[210:213], v[90:93]
	v_mfma_f32_16x16x32_bf16 v[70:73], v[168:171], v[218:221], v[70:73]
	v_mfma_f32_16x16x32_bf16 v[66:69], v[180:183], v[218:221], v[66:69]
	s_barrier
	s_add_i32 s58, s58, s5
	v_lshl_add_u64 v[222:223], s[46:47], 0, v[0:1]
	s_mov_b32 m0, s58
	ds_read_b128 v[184:187], v174 offset:16384
	ds_read_b128 v[188:191], v174 offset:17408
	ds_read_b128 v[192:195], v174 offset:18432
	ds_read_b128 v[196:199], v174 offset:19456
	ds_read_b128 v[200:203], v174 offset:20480
	ds_read_b128 v[210:213], v174 offset:21504
	ds_read_b128 v[214:217], v174 offset:22528
	ds_read_b128 v[218:221], v174 offset:23552
	global_load_lds_dwordx4 v[222:223], off
	s_add_i32 m0, s58, 0x2000
	s_add_u32 s58, s46, 0x80000
	v_lshl_add_u64 v[224:225], s[46:47], 0, v[158:159]
	s_addc_u32 s59, s47, 0
	s_add_i32 s60, s60, s5
	global_load_lds_dwordx4 v[224:225], off
	s_mov_b32 m0, s60
	v_lshl_add_u64 v[228:229], s[48:49], 0, v[160:161]
	global_load_lds_dwordx4 v0, s[58:59]
	s_add_i32 m0, s60, 0x2000
	s_nop 0
	global_load_lds_dwordx4 v158, s[58:59]
	v_lshl_add_u64 v[226:227], s[48:49], 0, v[162:163]
	s_mov_b32 m0, s14
	s_nop 0
	global_load_lds_dwordx4 v[226:227], off
	s_mov_b32 m0, s15
	s_nop 0
	global_load_lds_dwordx4 v[228:229], off
	s_waitcnt vmcnt(8) lgkmcnt(0)
	s_barrier
	v_mfma_f32_16x16x32_bf16 v[62:65], v[82:85], v[184:187], v[62:65]
	v_mfma_f32_16x16x32_bf16 v[58:61], v[98:101], v[184:187], v[58:61]
	v_mfma_f32_16x16x32_bf16 v[46:49], v[82:85], v[192:195], v[46:49]
	v_mfma_f32_16x16x32_bf16 v[42:45], v[98:101], v[192:195], v[42:45]
	v_mfma_f32_16x16x32_bf16 v[30:33], v[82:85], v[200:203], v[30:33]
	v_mfma_f32_16x16x32_bf16 v[26:29], v[98:101], v[200:203], v[26:29]
	v_mfma_f32_16x16x32_bf16 v[14:17], v[82:85], v[214:217], v[14:17]
	v_mfma_f32_16x16x32_bf16 v[10:13], v[98:101], v[214:217], v[10:13]
	v_mfma_f32_16x16x32_bf16 v[62:65], v[86:89], v[188:191], v[62:65]
	v_mfma_f32_16x16x32_bf16 v[58:61], v[102:105], v[188:191], v[58:61]
	v_mfma_f32_16x16x32_bf16 v[46:49], v[86:89], v[196:199], v[46:49]
	v_mfma_f32_16x16x32_bf16 v[42:45], v[102:105], v[196:199], v[42:45]
	v_mfma_f32_16x16x32_bf16 v[30:33], v[86:89], v[210:213], v[30:33]
	v_mfma_f32_16x16x32_bf16 v[26:29], v[102:105], v[210:213], v[26:29]
	v_mfma_f32_16x16x32_bf16 v[14:17], v[86:89], v[218:221], v[14:17]
	v_mfma_f32_16x16x32_bf16 v[10:13], v[102:105], v[218:221], v[10:13]
	v_mfma_f32_16x16x32_bf16 v[54:57], v[154:157], v[184:187], v[54:57]
	v_mfma_f32_16x16x32_bf16 v[50:53], v[176:179], v[184:187], v[50:53]
	v_mfma_f32_16x16x32_bf16 v[38:41], v[154:157], v[192:195], v[38:41]
	v_mfma_f32_16x16x32_bf16 v[34:37], v[176:179], v[192:195], v[34:37]
	v_mfma_f32_16x16x32_bf16 v[22:25], v[154:157], v[200:203], v[22:25]
	v_mfma_f32_16x16x32_bf16 v[18:21], v[176:179], v[200:203], v[18:21]
	v_mfma_f32_16x16x32_bf16 v[6:9], v[154:157], v[214:217], v[6:9]
	v_mfma_f32_16x16x32_bf16 v[2:5], v[176:179], v[214:217], v[2:5]
	v_mfma_f32_16x16x32_bf16 v[54:57], v[168:171], v[188:191], v[54:57]
	v_mfma_f32_16x16x32_bf16 v[50:53], v[180:183], v[188:191], v[50:53]
	v_mfma_f32_16x16x32_bf16 v[38:41], v[168:171], v[196:199], v[38:41]
	v_mfma_f32_16x16x32_bf16 v[34:37], v[180:183], v[196:199], v[34:37]
	v_mfma_f32_16x16x32_bf16 v[22:25], v[168:171], v[210:213], v[22:25]
	v_mfma_f32_16x16x32_bf16 v[18:21], v[180:183], v[210:213], v[18:21]
	v_mfma_f32_16x16x32_bf16 v[6:9], v[168:171], v[218:221], v[6:9]
	v_mfma_f32_16x16x32_bf16 v[2:5], v[180:183], v[218:221], v[2:5]
	s_barrier
	s_add_i32 s58, 0, 0x18000
	s_add_i32 s59, 0, 0x1c000
	ds_read_b128 v[82:85], v238
	ds_read_b128 v[86:89], v238 offset:1024
	ds_read_b128 v[98:101], v238 offset:2048
	ds_read_b128 v[102:105], v238 offset:3072
	ds_read_b128 v[154:157], v239
	ds_read_b128 v[168:171], v239 offset:1024
	ds_read_b128 v[176:179], v239 offset:2048
	ds_read_b128 v[180:183], v239 offset:3072
	s_add_u32 s48, s48, 0x80000
	s_addc_u32 s49, s49, 0
	s_mov_b32 m0, s16
	ds_read_b128 v[184:187], v174 offset:32768
	ds_read_b128 v[188:191], v174 offset:33792
	ds_read_b128 v[192:195], v174 offset:34816
	ds_read_b128 v[196:199], v174 offset:35840
	ds_read_b128 v[200:203], v174 offset:36864
	ds_read_b128 v[210:213], v174 offset:37888
	ds_read_b128 v[214:217], v174 offset:38912
	ds_read_b128 v[218:221], v174 offset:39936
	global_load_lds_dwordx4 v162, s[48:49]
	s_mov_b32 m0, s18
	s_nop 0
	global_load_lds_dwordx4 v160, s[48:49]
	s_waitcnt vmcnt(8) lgkmcnt(0)
	s_barrier
	v_mfma_f32_16x16x32_bf16 v[142:145], v[82:85], v[184:187], v[142:145]
	v_mfma_f32_16x16x32_bf16 v[138:141], v[98:101], v[184:187], v[138:141]
	v_mfma_f32_16x16x32_bf16 v[126:129], v[82:85], v[192:195], v[126:129]
	v_mfma_f32_16x16x32_bf16 v[122:125], v[98:101], v[192:195], v[122:125]
	v_mfma_f32_16x16x32_bf16 v[110:113], v[82:85], v[200:203], v[110:113]
	v_mfma_f32_16x16x32_bf16 v[106:109], v[98:101], v[200:203], v[106:109]
	v_mfma_f32_16x16x32_bf16 v[78:81], v[82:85], v[214:217], v[78:81]
	v_mfma_f32_16x16x32_bf16 v[74:77], v[98:101], v[214:217], v[74:77]
	v_mfma_f32_16x16x32_bf16 v[142:145], v[86:89], v[188:191], v[142:145]
	v_mfma_f32_16x16x32_bf16 v[138:141], v[102:105], v[188:191], v[138:141]
	v_mfma_f32_16x16x32_bf16 v[126:129], v[86:89], v[196:199], v[126:129]
	v_mfma_f32_16x16x32_bf16 v[122:125], v[102:105], v[196:199], v[122:125]
	v_mfma_f32_16x16x32_bf16 v[110:113], v[86:89], v[210:213], v[110:113]
	v_mfma_f32_16x16x32_bf16 v[106:109], v[102:105], v[210:213], v[106:109]
	v_mfma_f32_16x16x32_bf16 v[78:81], v[86:89], v[218:221], v[78:81]
	v_mfma_f32_16x16x32_bf16 v[74:77], v[102:105], v[218:221], v[74:77]
	v_mfma_f32_16x16x32_bf16 v[134:137], v[154:157], v[184:187], v[134:137]
	v_mfma_f32_16x16x32_bf16 v[130:133], v[176:179], v[184:187], v[130:133]
	v_mfma_f32_16x16x32_bf16 v[118:121], v[154:157], v[192:195], v[118:121]
	v_mfma_f32_16x16x32_bf16 v[114:117], v[176:179], v[192:195], v[114:117]
	v_mfma_f32_16x16x32_bf16 v[94:97], v[154:157], v[200:203], v[94:97]
	v_mfma_f32_16x16x32_bf16 v[90:93], v[176:179], v[200:203], v[90:93]
	v_mfma_f32_16x16x32_bf16 v[70:73], v[154:157], v[214:217], v[70:73]
	v_mfma_f32_16x16x32_bf16 v[66:69], v[176:179], v[214:217], v[66:69]
	v_mfma_f32_16x16x32_bf16 v[134:137], v[168:171], v[188:191], v[134:137]
	v_mfma_f32_16x16x32_bf16 v[130:133], v[180:183], v[188:191], v[130:133]
	v_mfma_f32_16x16x32_bf16 v[118:121], v[168:171], v[196:199], v[118:121]
	v_mfma_f32_16x16x32_bf16 v[114:117], v[180:183], v[196:199], v[114:117]
	v_mfma_f32_16x16x32_bf16 v[94:97], v[168:171], v[210:213], v[94:97]
	v_mfma_f32_16x16x32_bf16 v[90:93], v[180:183], v[210:213], v[90:93]
	v_mfma_f32_16x16x32_bf16 v[70:73], v[168:171], v[218:221], v[70:73]
	v_mfma_f32_16x16x32_bf16 v[66:69], v[180:183], v[218:221], v[66:69]
	s_barrier
	s_add_i32 s48, s58, s5
	v_lshl_add_u64 v[222:223], v[222:223], 0, s[34:35]
	s_mov_b32 m0, s48
	ds_read_b128 v[184:187], v174 offset:49152
	ds_read_b128 v[188:191], v174 offset:50176
	ds_read_b128 v[192:195], v174 offset:51200
	ds_read_b128 v[196:199], v174 offset:52224
	ds_read_b128 v[200:203], v174 offset:53248
	ds_read_b128 v[210:213], v174 offset:54272
	ds_read_b128 v[214:217], v174 offset:55296
	ds_read_b128 v[218:221], v174 offset:56320
	global_load_lds_dwordx4 v[222:223], off
	s_add_i32 m0, s48, 0x2000
	s_add_u32 s46, s46, 0x80080
	v_lshl_add_u64 v[222:223], v[224:225], 0, s[34:35]
	s_addc_u32 s47, s47, 0
	s_add_i32 s48, s59, s5
	global_load_lds_dwordx4 v[222:223], off
	s_mov_b32 m0, s48
	s_nop 0
	global_load_lds_dwordx4 v0, s[46:47]
	s_add_i32 m0, s48, 0x2000
	s_nop 0
	global_load_lds_dwordx4 v158, s[46:47]
	v_lshl_add_u64 v[222:223], v[226:227], 0, s[34:35]
	s_mov_b32 m0, s25
	s_nop 0
	global_load_lds_dwordx4 v[222:223], off
	v_lshl_add_u64 v[222:223], v[228:229], 0, s[34:35]
	s_mov_b32 m0, s33
	s_nop 0
	global_load_lds_dwordx4 v[222:223], off
	s_waitcnt vmcnt(8) lgkmcnt(0)
	s_barrier
	v_mfma_f32_16x16x32_bf16 v[62:65], v[82:85], v[184:187], v[62:65]
	v_mfma_f32_16x16x32_bf16 v[58:61], v[98:101], v[184:187], v[58:61]
	v_mfma_f32_16x16x32_bf16 v[46:49], v[82:85], v[192:195], v[46:49]
	v_mfma_f32_16x16x32_bf16 v[42:45], v[98:101], v[192:195], v[42:45]
	v_mfma_f32_16x16x32_bf16 v[30:33], v[82:85], v[200:203], v[30:33]
	v_mfma_f32_16x16x32_bf16 v[26:29], v[98:101], v[200:203], v[26:29]
	v_mfma_f32_16x16x32_bf16 v[14:17], v[82:85], v[214:217], v[14:17]
	v_mfma_f32_16x16x32_bf16 v[10:13], v[98:101], v[214:217], v[10:13]
	v_mfma_f32_16x16x32_bf16 v[62:65], v[86:89], v[188:191], v[62:65]
	v_mfma_f32_16x16x32_bf16 v[58:61], v[102:105], v[188:191], v[58:61]
	v_mfma_f32_16x16x32_bf16 v[46:49], v[86:89], v[196:199], v[46:49]
	v_mfma_f32_16x16x32_bf16 v[42:45], v[102:105], v[196:199], v[42:45]
	v_mfma_f32_16x16x32_bf16 v[30:33], v[86:89], v[210:213], v[30:33]
	v_mfma_f32_16x16x32_bf16 v[26:29], v[102:105], v[210:213], v[26:29]
	v_mfma_f32_16x16x32_bf16 v[14:17], v[86:89], v[218:221], v[14:17]
	v_mfma_f32_16x16x32_bf16 v[10:13], v[102:105], v[218:221], v[10:13]
	v_mfma_f32_16x16x32_bf16 v[54:57], v[154:157], v[184:187], v[54:57]
	v_mfma_f32_16x16x32_bf16 v[50:53], v[176:179], v[184:187], v[50:53]
	v_mfma_f32_16x16x32_bf16 v[38:41], v[154:157], v[192:195], v[38:41]
	v_mfma_f32_16x16x32_bf16 v[34:37], v[176:179], v[192:195], v[34:37]
	v_mfma_f32_16x16x32_bf16 v[22:25], v[154:157], v[200:203], v[22:25]
	v_mfma_f32_16x16x32_bf16 v[18:21], v[176:179], v[200:203], v[18:21]
	v_mfma_f32_16x16x32_bf16 v[6:9], v[154:157], v[214:217], v[6:9]
	v_mfma_f32_16x16x32_bf16 v[2:5], v[176:179], v[214:217], v[2:5]
	v_mfma_f32_16x16x32_bf16 v[54:57], v[168:171], v[188:191], v[54:57]
	v_mfma_f32_16x16x32_bf16 v[50:53], v[180:183], v[188:191], v[50:53]
	v_mfma_f32_16x16x32_bf16 v[38:41], v[168:171], v[196:199], v[38:41]
	v_mfma_f32_16x16x32_bf16 v[34:37], v[180:183], v[196:199], v[34:37]
	v_mfma_f32_16x16x32_bf16 v[22:25], v[168:171], v[210:213], v[22:25]
	v_mfma_f32_16x16x32_bf16 v[18:21], v[180:183], v[210:213], v[18:21]
	v_mfma_f32_16x16x32_bf16 v[6:9], v[168:171], v[218:221], v[6:9]
	v_mfma_f32_16x16x32_bf16 v[2:5], v[180:183], v[218:221], v[2:5]
	s_barrier
	s_add_i32 s57, s57, 2
	s_add_u32 s44, s44, 0x100
	s_addc_u32 s45, s45, 0
	s_add_u32 s55, s55, 0x100
	s_addc_u32 s56, s56, 0
	s_cmp_gt_u32 s57, 29
	s_cbranch_scc0 .LBB0_516
	s_setprio 0
	s_and_b64 vcc, exec, s[10:11]
	s_cbranch_vccz .LBB0_519
	s_barrier

.LBB0_604:
	s_add_u32 s22, s6, 0xfff80080
	s_addc_u32 s23, s7, -1
	s_add_i32 s54, 0, 0x10000
	s_cmp_eq_u32 s53, 28
	s_cselect_b32 s47, s18, s23
	s_cselect_b32 s46, s19, s22
	s_cselect_b32 s23, s21, s52
	s_cselect_b32 s22, s25, s41
	s_add_i32 s56, 0, 0x14000
	ds_read_b128 v[130:133], v236
	ds_read_b128 v[134:137], v236 offset:1024
	ds_read_b128 v[154:157], v236 offset:2048
	ds_read_b128 v[162:165], v236 offset:3072
	ds_read_b128 v[166:169], v237
	ds_read_b128 v[170:173], v237 offset:1024
	ds_read_b128 v[180:183], v237 offset:2048
	ds_read_b128 v[184:187], v237 offset:3072
	s_add_i32 m0, s16, 0xc000
	ds_read_b128 v[188:191], v179
	ds_read_b128 v[192:195], v179 offset:1024
	ds_read_b128 v[196:199], v179 offset:2048
	ds_read_b128 v[200:203], v179 offset:3072
	ds_read_b128 v[210:213], v179 offset:4096
	ds_read_b128 v[214:217], v179 offset:5120
	ds_read_b128 v[218:221], v179 offset:6144
	ds_read_b128 v[222:225], v179 offset:7168
	global_load_lds_dwordx4 v158, s[6:7]
	s_add_i32 m0, s16, 0xe000
	s_nop 0
	global_load_lds_dwordx4 v160, s[6:7]
	s_waitcnt vmcnt(8) lgkmcnt(0)
	s_barrier
	v_mfma_f32_16x16x32_bf16 v[126:129], v[130:133], v[188:191], v[126:129]
	v_mfma_f32_16x16x32_bf16 v[122:125], v[154:157], v[188:191], v[122:125]
	v_mfma_f32_16x16x32_bf16 v[110:113], v[130:133], v[196:199], v[110:113]
	v_mfma_f32_16x16x32_bf16 v[106:109], v[154:157], v[196:199], v[106:109]
	v_mfma_f32_16x16x32_bf16 v[94:97], v[130:133], v[210:213], v[94:97]
	v_mfma_f32_16x16x32_bf16 v[90:93], v[154:157], v[210:213], v[90:93]
	v_mfma_f32_16x16x32_bf16 v[78:81], v[130:133], v[218:221], v[78:81]
	v_mfma_f32_16x16x32_bf16 v[74:77], v[154:157], v[218:221], v[74:77]
	v_mfma_f32_16x16x32_bf16 v[126:129], v[134:137], v[192:195], v[126:129]
	v_mfma_f32_16x16x32_bf16 v[122:125], v[162:165], v[192:195], v[122:125]
	v_mfma_f32_16x16x32_bf16 v[110:113], v[134:137], v[200:203], v[110:113]
	v_mfma_f32_16x16x32_bf16 v[106:109], v[162:165], v[200:203], v[106:109]
	v_mfma_f32_16x16x32_bf16 v[94:97], v[134:137], v[214:217], v[94:97]
	v_mfma_f32_16x16x32_bf16 v[90:93], v[162:165], v[214:217], v[90:93]
	v_mfma_f32_16x16x32_bf16 v[78:81], v[134:137], v[222:225], v[78:81]
	v_mfma_f32_16x16x32_bf16 v[74:77], v[162:165], v[222:225], v[74:77]
	v_mfma_f32_16x16x32_bf16 v[118:121], v[166:169], v[188:191], v[118:121]
	v_mfma_f32_16x16x32_bf16 v[114:117], v[180:183], v[188:191], v[114:117]
	v_mfma_f32_16x16x32_bf16 v[102:105], v[166:169], v[196:199], v[102:105]
	v_mfma_f32_16x16x32_bf16 v[98:101], v[180:183], v[196:199], v[98:101]
	v_mfma_f32_16x16x32_bf16 v[86:89], v[166:169], v[210:213], v[86:89]
	v_mfma_f32_16x16x32_bf16 v[82:85], v[180:183], v[210:213], v[82:85]
	v_mfma_f32_16x16x32_bf16 v[70:73], v[166:169], v[218:221], v[70:73]
	v_mfma_f32_16x16x32_bf16 v[66:69], v[180:183], v[218:221], v[66:69]
	v_mfma_f32_16x16x32_bf16 v[118:121], v[170:173], v[192:195], v[118:121]
	v_mfma_f32_16x16x32_bf16 v[114:117], v[184:187], v[192:195], v[114:117]
	v_mfma_f32_16x16x32_bf16 v[102:105], v[170:173], v[200:203], v[102:105]
	v_mfma_f32_16x16x32_bf16 v[98:101], v[184:187], v[200:203], v[98:101]
	v_mfma_f32_16x16x32_bf16 v[86:89], v[170:173], v[214:217], v[86:89]
	v_mfma_f32_16x16x32_bf16 v[82:85], v[184:187], v[214:217], v[82:85]
	v_mfma_f32_16x16x32_bf16 v[70:73], v[170:173], v[222:225], v[70:73]
	v_mfma_f32_16x16x32_bf16 v[66:69], v[184:187], v[222:225], v[66:69]
	s_barrier
	s_add_i32 s54, s54, s15
	v_lshl_add_u64 v[226:227], s[22:23], 0, v[142:143]
	s_mov_b32 m0, s54
	ds_read_b128 v[188:191], v179 offset:16384
	ds_read_b128 v[192:195], v179 offset:17408
	ds_read_b128 v[196:199], v179 offset:18432
	ds_read_b128 v[200:203], v179 offset:19456
	ds_read_b128 v[210:213], v179 offset:20480
	ds_read_b128 v[214:217], v179 offset:21504
	ds_read_b128 v[218:221], v179 offset:22528
	ds_read_b128 v[222:225], v179 offset:23552
	global_load_lds_dwordx4 v[226:227], off
	s_add_i32 m0, s54, 0x2000
	s_add_u32 s54, s22, 0x80000
	v_lshl_add_u64 v[228:229], s[22:23], 0, v[138:139]
	s_addc_u32 s55, s23, 0
	s_add_i32 s56, s56, s15
	global_load_lds_dwordx4 v[228:229], off
	s_mov_b32 m0, s56
	v_lshl_add_u64 v[232:233], s[46:47], 0, v[140:141]
	global_load_lds_dwordx4 v142, s[54:55]
	s_add_i32 m0, s56, 0x2000
	s_nop 0
	global_load_lds_dwordx4 v138, s[54:55]
	v_lshl_add_u64 v[230:231], s[46:47], 0, v[144:145]
	s_mov_b32 m0, s16
	s_nop 0
	global_load_lds_dwordx4 v[230:231], off
	s_mov_b32 m0, s33
	s_nop 0
	global_load_lds_dwordx4 v[232:233], off
	s_waitcnt vmcnt(8) lgkmcnt(0)
	s_barrier
	v_mfma_f32_16x16x32_bf16 v[62:65], v[130:133], v[188:191], v[62:65]
	v_mfma_f32_16x16x32_bf16 v[58:61], v[154:157], v[188:191], v[58:61]
	v_mfma_f32_16x16x32_bf16 v[46:49], v[130:133], v[196:199], v[46:49]
	v_mfma_f32_16x16x32_bf16 v[42:45], v[154:157], v[196:199], v[42:45]
	v_mfma_f32_16x16x32_bf16 v[30:33], v[130:133], v[210:213], v[30:33]
	v_mfma_f32_16x16x32_bf16 v[26:29], v[154:157], v[210:213], v[26:29]
	v_mfma_f32_16x16x32_bf16 v[14:17], v[130:133], v[218:221], v[14:17]
	v_mfma_f32_16x16x32_bf16 v[10:13], v[154:157], v[218:221], v[10:13]
	v_mfma_f32_16x16x32_bf16 v[62:65], v[134:137], v[192:195], v[62:65]
	v_mfma_f32_16x16x32_bf16 v[58:61], v[162:165], v[192:195], v[58:61]
	v_mfma_f32_16x16x32_bf16 v[46:49], v[134:137], v[200:203], v[46:49]
	v_mfma_f32_16x16x32_bf16 v[42:45], v[162:165], v[200:203], v[42:45]
	v_mfma_f32_16x16x32_bf16 v[30:33], v[134:137], v[214:217], v[30:33]
	v_mfma_f32_16x16x32_bf16 v[26:29], v[162:165], v[214:217], v[26:29]
	v_mfma_f32_16x16x32_bf16 v[14:17], v[134:137], v[222:225], v[14:17]
	v_mfma_f32_16x16x32_bf16 v[10:13], v[162:165], v[222:225], v[10:13]
	v_mfma_f32_16x16x32_bf16 v[54:57], v[166:169], v[188:191], v[54:57]
	v_mfma_f32_16x16x32_bf16 v[50:53], v[180:183], v[188:191], v[50:53]
	v_mfma_f32_16x16x32_bf16 v[38:41], v[166:169], v[196:199], v[38:41]
	v_mfma_f32_16x16x32_bf16 v[34:37], v[180:183], v[196:199], v[34:37]
	v_mfma_f32_16x16x32_bf16 v[22:25], v[166:169], v[210:213], v[22:25]
	v_mfma_f32_16x16x32_bf16 v[18:21], v[180:183], v[210:213], v[18:21]
	v_mfma_f32_16x16x32_bf16 v[6:9], v[166:169], v[218:221], v[6:9]
	v_mfma_f32_16x16x32_bf16 v[2:5], v[180:183], v[218:221], v[2:5]
	v_mfma_f32_16x16x32_bf16 v[54:57], v[170:173], v[192:195], v[54:57]
	v_mfma_f32_16x16x32_bf16 v[50:53], v[184:187], v[192:195], v[50:53]
	v_mfma_f32_16x16x32_bf16 v[38:41], v[170:173], v[200:203], v[38:41]
	v_mfma_f32_16x16x32_bf16 v[34:37], v[184:187], v[200:203], v[34:37]
	v_mfma_f32_16x16x32_bf16 v[22:25], v[170:173], v[214:217], v[22:25]
	v_mfma_f32_16x16x32_bf16 v[18:21], v[184:187], v[214:217], v[18:21]
	v_mfma_f32_16x16x32_bf16 v[6:9], v[170:173], v[222:225], v[6:9]
	v_mfma_f32_16x16x32_bf16 v[2:5], v[184:187], v[222:225], v[2:5]
	s_barrier
	s_add_i32 s54, 0, 0x18000
	s_add_i32 s55, 0, 0x1c000
	ds_read_b128 v[130:133], v238
	ds_read_b128 v[134:137], v238 offset:1024
	ds_read_b128 v[154:157], v238 offset:2048
	ds_read_b128 v[162:165], v238 offset:3072
	ds_read_b128 v[166:169], v239
	ds_read_b128 v[170:173], v239 offset:1024
	ds_read_b128 v[180:183], v239 offset:2048
	ds_read_b128 v[184:187], v239 offset:3072
	s_add_u32 s46, s46, 0x80000
	s_addc_u32 s47, s47, 0
	s_mov_b32 m0, s37
	ds_read_b128 v[188:191], v179 offset:32768
	ds_read_b128 v[192:195], v179 offset:33792
	ds_read_b128 v[196:199], v179 offset:34816
	ds_read_b128 v[200:203], v179 offset:35840
	ds_read_b128 v[210:213], v179 offset:36864
	ds_read_b128 v[214:217], v179 offset:37888
	ds_read_b128 v[218:221], v179 offset:38912
	ds_read_b128 v[222:225], v179 offset:39936
	global_load_lds_dwordx4 v144, s[46:47]
	s_mov_b32 m0, s48
	s_nop 0
	global_load_lds_dwordx4 v140, s[46:47]
	s_waitcnt vmcnt(8) lgkmcnt(0)
	s_barrier
	v_mfma_f32_16x16x32_bf16 v[126:129], v[130:133], v[188:191], v[126:129]
	v_mfma_f32_16x16x32_bf16 v[122:125], v[154:157], v[188:191], v[122:125]
	v_mfma_f32_16x16x32_bf16 v[110:113], v[130:133], v[196:199], v[110:113]
	v_mfma_f32_16x16x32_bf16 v[106:109], v[154:157], v[196:199], v[106:109]
	v_mfma_f32_16x16x32_bf16 v[94:97], v[130:133], v[210:213], v[94:97]
	v_mfma_f32_16x16x32_bf16 v[90:93], v[154:157], v[210:213], v[90:93]
	v_mfma_f32_16x16x32_bf16 v[78:81], v[130:133], v[218:221], v[78:81]
	v_mfma_f32_16x16x32_bf16 v[74:77], v[154:157], v[218:221], v[74:77]
	v_mfma_f32_16x16x32_bf16 v[126:129], v[134:137], v[192:195], v[126:129]
	v_mfma_f32_16x16x32_bf16 v[122:125], v[162:165], v[192:195], v[122:125]
	v_mfma_f32_16x16x32_bf16 v[110:113], v[134:137], v[200:203], v[110:113]
	v_mfma_f32_16x16x32_bf16 v[106:109], v[162:165], v[200:203], v[106:109]
	v_mfma_f32_16x16x32_bf16 v[94:97], v[134:137], v[214:217], v[94:97]
	v_mfma_f32_16x16x32_bf16 v[90:93], v[162:165], v[214:217], v[90:93]
	v_mfma_f32_16x16x32_bf16 v[78:81], v[134:137], v[222:225], v[78:81]
	v_mfma_f32_16x16x32_bf16 v[74:77], v[162:165], v[222:225], v[74:77]
	v_mfma_f32_16x16x32_bf16 v[118:121], v[166:169], v[188:191], v[118:121]
	v_mfma_f32_16x16x32_bf16 v[114:117], v[180:183], v[188:191], v[114:117]
	v_mfma_f32_16x16x32_bf16 v[102:105], v[166:169], v[196:199], v[102:105]
	v_mfma_f32_16x16x32_bf16 v[98:101], v[180:183], v[196:199], v[98:101]
	v_mfma_f32_16x16x32_bf16 v[86:89], v[166:169], v[210:213], v[86:89]
	v_mfma_f32_16x16x32_bf16 v[82:85], v[180:183], v[210:213], v[82:85]
	v_mfma_f32_16x16x32_bf16 v[70:73], v[166:169], v[218:221], v[70:73]
	v_mfma_f32_16x16x32_bf16 v[66:69], v[180:183], v[218:221], v[66:69]
	v_mfma_f32_16x16x32_bf16 v[118:121], v[170:173], v[192:195], v[118:121]
	v_mfma_f32_16x16x32_bf16 v[114:117], v[184:187], v[192:195], v[114:117]
	v_mfma_f32_16x16x32_bf16 v[102:105], v[170:173], v[200:203], v[102:105]
	v_mfma_f32_16x16x32_bf16 v[98:101], v[184:187], v[200:203], v[98:101]
	v_mfma_f32_16x16x32_bf16 v[86:89], v[170:173], v[214:217], v[86:89]
	v_mfma_f32_16x16x32_bf16 v[82:85], v[184:187], v[214:217], v[82:85]
	v_mfma_f32_16x16x32_bf16 v[70:73], v[170:173], v[222:225], v[70:73]
	v_mfma_f32_16x16x32_bf16 v[66:69], v[184:187], v[222:225], v[66:69]
	s_barrier
	s_add_i32 s46, s54, s15
	v_lshl_add_u64 v[226:227], v[226:227], 0, s[34:35]
	s_mov_b32 m0, s46
	ds_read_b128 v[188:191], v179 offset:49152
	ds_read_b128 v[192:195], v179 offset:50176
	ds_read_b128 v[196:199], v179 offset:51200
	ds_read_b128 v[200:203], v179 offset:52224
	ds_read_b128 v[210:213], v179 offset:53248
	ds_read_b128 v[214:217], v179 offset:54272
	ds_read_b128 v[218:221], v179 offset:55296
	ds_read_b128 v[222:225], v179 offset:56320
	global_load_lds_dwordx4 v[226:227], off
	s_add_i32 m0, s46, 0x2000
	s_add_u32 s22, s22, 0x80080
	v_lshl_add_u64 v[226:227], v[228:229], 0, s[34:35]
	s_addc_u32 s23, s23, 0
	s_add_i32 s46, s55, s15
	global_load_lds_dwordx4 v[226:227], off
	s_mov_b32 m0, s46
	s_nop 0
	global_load_lds_dwordx4 v142, s[22:23]
	s_add_i32 m0, s46, 0x2000
	s_nop 0
	global_load_lds_dwordx4 v138, s[22:23]
	v_lshl_add_u64 v[226:227], v[230:231], 0, s[34:35]
	s_mov_b32 m0, s49
	s_nop 0
	global_load_lds_dwordx4 v[226:227], off
	v_lshl_add_u64 v[226:227], v[232:233], 0, s[34:35]
	s_mov_b32 m0, s50
	s_nop 0
	global_load_lds_dwordx4 v[226:227], off
	s_waitcnt vmcnt(8) lgkmcnt(0)
	s_barrier
	v_mfma_f32_16x16x32_bf16 v[62:65], v[130:133], v[188:191], v[62:65]
	v_mfma_f32_16x16x32_bf16 v[58:61], v[154:157], v[188:191], v[58:61]
	v_mfma_f32_16x16x32_bf16 v[46:49], v[130:133], v[196:199], v[46:49]
	v_mfma_f32_16x16x32_bf16 v[42:45], v[154:157], v[196:199], v[42:45]
	v_mfma_f32_16x16x32_bf16 v[30:33], v[130:133], v[210:213], v[30:33]
	v_mfma_f32_16x16x32_bf16 v[26:29], v[154:157], v[210:213], v[26:29]
	v_mfma_f32_16x16x32_bf16 v[14:17], v[130:133], v[218:221], v[14:17]
	v_mfma_f32_16x16x32_bf16 v[10:13], v[154:157], v[218:221], v[10:13]
	v_mfma_f32_16x16x32_bf16 v[62:65], v[134:137], v[192:195], v[62:65]
	v_mfma_f32_16x16x32_bf16 v[58:61], v[162:165], v[192:195], v[58:61]
	v_mfma_f32_16x16x32_bf16 v[46:49], v[134:137], v[200:203], v[46:49]
	v_mfma_f32_16x16x32_bf16 v[42:45], v[162:165], v[200:203], v[42:45]
	v_mfma_f32_16x16x32_bf16 v[30:33], v[134:137], v[214:217], v[30:33]
	v_mfma_f32_16x16x32_bf16 v[26:29], v[162:165], v[214:217], v[26:29]
	v_mfma_f32_16x16x32_bf16 v[14:17], v[134:137], v[222:225], v[14:17]
	v_mfma_f32_16x16x32_bf16 v[10:13], v[162:165], v[222:225], v[10:13]
	v_mfma_f32_16x16x32_bf16 v[54:57], v[166:169], v[188:191], v[54:57]
	v_mfma_f32_16x16x32_bf16 v[50:53], v[180:183], v[188:191], v[50:53]
	v_mfma_f32_16x16x32_bf16 v[38:41], v[166:169], v[196:199], v[38:41]
	v_mfma_f32_16x16x32_bf16 v[34:37], v[180:183], v[196:199], v[34:37]
	v_mfma_f32_16x16x32_bf16 v[22:25], v[166:169], v[210:213], v[22:25]
	v_mfma_f32_16x16x32_bf16 v[18:21], v[180:183], v[210:213], v[18:21]
	v_mfma_f32_16x16x32_bf16 v[6:9], v[166:169], v[218:221], v[6:9]
	v_mfma_f32_16x16x32_bf16 v[2:5], v[180:183], v[218:221], v[2:5]
	v_mfma_f32_16x16x32_bf16 v[54:57], v[170:173], v[192:195], v[54:57]
	v_mfma_f32_16x16x32_bf16 v[50:53], v[184:187], v[192:195], v[50:53]
	v_mfma_f32_16x16x32_bf16 v[38:41], v[170:173], v[200:203], v[38:41]
	v_mfma_f32_16x16x32_bf16 v[34:37], v[184:187], v[200:203], v[34:37]
	v_mfma_f32_16x16x32_bf16 v[22:25], v[170:173], v[214:217], v[22:25]
	v_mfma_f32_16x16x32_bf16 v[18:21], v[184:187], v[214:217], v[18:21]
	v_mfma_f32_16x16x32_bf16 v[6:9], v[170:173], v[222:225], v[6:9]
	v_mfma_f32_16x16x32_bf16 v[2:5], v[184:187], v[222:225], v[2:5]
	s_barrier
	s_add_i32 s53, s53, 2
	s_add_u32 s6, s6, 0x100
	s_addc_u32 s7, s7, 0
	s_add_u32 s41, s41, 0x100
	s_addc_u32 s52, s52, 0
	s_cmp_gt_u32 s53, 29
	s_cbranch_scc0 .LBB0_604
	s_setprio 0
	s_and_b64 vcc, exec, s[12:13]
	s_cbranch_vccz .LBB0_607
	s_barrier

.Lgprio3:
	v_add_u32_e32 v236, 0x10000, v176
	v_add_u32_e32 v237, 0x14000, v176
	v_add_u32_e32 v238, 0x18000, v176
	v_add_u32_e32 v239, 0x1c000, v176
.LBB0_728:
	s_add_u32 s42, s22, 0x100
	s_addc_u32 s43, s23, 0
	s_add_i32 s50, 0, 0x10000
	s_cmpk_eq_i32 s25, 0x54
	s_cselect_b32 s49, s21, s43
	s_cselect_b32 s48, s20, s42
	s_cselect_b32 s47, s45, s19
	s_cselect_b32 s46, s44, s18
	s_add_i32 s51, 0, 0x14000
	ds_read_b128 v[42:45], v236
	ds_read_b128 v[46:49], v236 offset:1024
	ds_read_b128 v[50:53], v236 offset:2048
	ds_read_b128 v[54:57], v236 offset:3072
	ds_read_b128 v[154:157], v237
	ds_read_b128 v[168:171], v237 offset:1024
	ds_read_b128 v[172:175], v237 offset:2048
	ds_read_b128 v[180:183], v237 offset:3072
	s_add_i32 m0, s33, 0xc000
	ds_read_b128 v[184:187], v178
	ds_read_b128 v[188:191], v178 offset:1024
	ds_read_b128 v[192:195], v178 offset:2048
	ds_read_b128 v[196:199], v178 offset:3072
	ds_read_b128 v[200:203], v178 offset:4096
	ds_read_b128 v[210:213], v178 offset:5120
	ds_read_b128 v[214:217], v178 offset:6144
	ds_read_b128 v[218:221], v178 offset:7168
	global_load_lds_dwordx4 v164, s[22:23]
	s_add_i32 m0, s33, 0xe000
	s_nop 0
	global_load_lds_dwordx4 v166, s[22:23]
	s_waitcnt vmcnt(8) lgkmcnt(0)
	s_barrier
	v_mfma_f32_16x16x32_bf16 v[142:145], v[42:45], v[184:187], v[142:145]
	v_mfma_f32_16x16x32_bf16 v[138:141], v[50:53], v[184:187], v[138:141]
	v_mfma_f32_16x16x32_bf16 v[126:129], v[42:45], v[192:195], v[126:129]
	v_mfma_f32_16x16x32_bf16 v[122:125], v[50:53], v[192:195], v[122:125]
	v_mfma_f32_16x16x32_bf16 v[110:113], v[42:45], v[200:203], v[110:113]
	v_mfma_f32_16x16x32_bf16 v[106:109], v[50:53], v[200:203], v[106:109]
	v_mfma_f32_16x16x32_bf16 v[94:97], v[42:45], v[214:217], v[94:97]
	v_mfma_f32_16x16x32_bf16 v[90:93], v[50:53], v[214:217], v[90:93]
	v_mfma_f32_16x16x32_bf16 v[142:145], v[46:49], v[188:191], v[142:145]
	v_mfma_f32_16x16x32_bf16 v[138:141], v[54:57], v[188:191], v[138:141]
	v_mfma_f32_16x16x32_bf16 v[126:129], v[46:49], v[196:199], v[126:129]
	v_mfma_f32_16x16x32_bf16 v[122:125], v[54:57], v[196:199], v[122:125]
	v_mfma_f32_16x16x32_bf16 v[110:113], v[46:49], v[210:213], v[110:113]
	v_mfma_f32_16x16x32_bf16 v[106:109], v[54:57], v[210:213], v[106:109]
	v_mfma_f32_16x16x32_bf16 v[94:97], v[46:49], v[218:221], v[94:97]
	v_mfma_f32_16x16x32_bf16 v[90:93], v[54:57], v[218:221], v[90:93]
	v_mfma_f32_16x16x32_bf16 v[134:137], v[154:157], v[184:187], v[134:137]
	v_mfma_f32_16x16x32_bf16 v[130:133], v[172:175], v[184:187], v[130:133]
	v_mfma_f32_16x16x32_bf16 v[118:121], v[154:157], v[192:195], v[118:121]
	v_mfma_f32_16x16x32_bf16 v[114:117], v[172:175], v[192:195], v[114:117]
	v_mfma_f32_16x16x32_bf16 v[102:105], v[154:157], v[200:203], v[102:105]
	v_mfma_f32_16x16x32_bf16 v[98:101], v[172:175], v[200:203], v[98:101]
	v_mfma_f32_16x16x32_bf16 v[86:89], v[154:157], v[214:217], v[86:89]
	v_mfma_f32_16x16x32_bf16 v[82:85], v[172:175], v[214:217], v[82:85]
	v_mfma_f32_16x16x32_bf16 v[134:137], v[168:171], v[188:191], v[134:137]
	v_mfma_f32_16x16x32_bf16 v[130:133], v[180:183], v[188:191], v[130:133]
	v_mfma_f32_16x16x32_bf16 v[118:121], v[168:171], v[196:199], v[118:121]
	v_mfma_f32_16x16x32_bf16 v[114:117], v[180:183], v[196:199], v[114:117]
	v_mfma_f32_16x16x32_bf16 v[102:105], v[168:171], v[210:213], v[102:105]
	v_mfma_f32_16x16x32_bf16 v[98:101], v[180:183], v[210:213], v[98:101]
	v_mfma_f32_16x16x32_bf16 v[86:89], v[168:171], v[218:221], v[86:89]
	v_mfma_f32_16x16x32_bf16 v[82:85], v[180:183], v[218:221], v[82:85]
	s_barrier
	s_add_i32 s22, s50, s16
	v_lshl_add_u64 v[222:223], s[46:47], 0, v[0:1]
	s_mov_b32 m0, s22
	ds_read_b128 v[184:187], v178 offset:16384
	ds_read_b128 v[188:191], v178 offset:17408
	ds_read_b128 v[192:195], v178 offset:18432
	ds_read_b128 v[196:199], v178 offset:19456
	ds_read_b128 v[200:203], v178 offset:20480
	ds_read_b128 v[210:213], v178 offset:21504
	ds_read_b128 v[214:217], v178 offset:22528
	ds_read_b128 v[218:221], v178 offset:23552
	global_load_lds_dwordx4 v[222:223], off
	s_add_i32 m0, s22, 0x2000
	s_add_u32 s22, s46, 0x160000
	v_lshl_add_u64 v[224:225], s[46:47], 0, v[158:159]
	s_addc_u32 s23, s47, 0
	s_add_i32 s50, s51, s16
	global_load_lds_dwordx4 v[224:225], off
	s_mov_b32 m0, s50
	v_lshl_add_u64 v[228:229], s[48:49], 0, v[160:161]
	global_load_lds_dwordx4 v0, s[22:23]
	s_add_i32 m0, s50, 0x2000
	s_nop 0
	global_load_lds_dwordx4 v158, s[22:23]
	v_lshl_add_u64 v[226:227], s[48:49], 0, v[162:163]
	s_mov_b32 m0, s33
	s_nop 0
	global_load_lds_dwordx4 v[226:227], off
	s_mov_b32 m0, s37
	s_nop 0
	global_load_lds_dwordx4 v[228:229], off
	s_waitcnt vmcnt(8) lgkmcnt(0)
	s_barrier
	v_mfma_f32_16x16x32_bf16 v[78:81], v[42:45], v[184:187], v[78:81]
	v_mfma_f32_16x16x32_bf16 v[74:77], v[50:53], v[184:187], v[74:77]
	v_mfma_f32_16x16x32_bf16 v[62:65], v[42:45], v[192:195], v[62:65]
	v_mfma_f32_16x16x32_bf16 v[58:61], v[50:53], v[192:195], v[58:61]
	v_mfma_f32_16x16x32_bf16 v[30:33], v[42:45], v[200:203], v[30:33]
	v_mfma_f32_16x16x32_bf16 v[26:29], v[50:53], v[200:203], v[26:29]
	v_mfma_f32_16x16x32_bf16 v[14:17], v[42:45], v[214:217], v[14:17]
	v_mfma_f32_16x16x32_bf16 v[10:13], v[50:53], v[214:217], v[10:13]
	v_mfma_f32_16x16x32_bf16 v[78:81], v[46:49], v[188:191], v[78:81]
	v_mfma_f32_16x16x32_bf16 v[74:77], v[54:57], v[188:191], v[74:77]
	v_mfma_f32_16x16x32_bf16 v[62:65], v[46:49], v[196:199], v[62:65]
	v_mfma_f32_16x16x32_bf16 v[58:61], v[54:57], v[196:199], v[58:61]
	v_mfma_f32_16x16x32_bf16 v[30:33], v[46:49], v[210:213], v[30:33]
	v_mfma_f32_16x16x32_bf16 v[26:29], v[54:57], v[210:213], v[26:29]
	v_mfma_f32_16x16x32_bf16 v[14:17], v[46:49], v[218:221], v[14:17]
	v_mfma_f32_16x16x32_bf16 v[10:13], v[54:57], v[218:221], v[10:13]
	v_mfma_f32_16x16x32_bf16 v[38:41], v[154:157], v[192:195], v[38:41]
	v_mfma_f32_16x16x32_bf16 v[34:37], v[172:175], v[192:195], v[34:37]
	v_mfma_f32_16x16x32_bf16 v[22:25], v[154:157], v[200:203], v[22:25]
	v_mfma_f32_16x16x32_bf16 v[18:21], v[172:175], v[200:203], v[18:21]
	v_mfma_f32_16x16x32_bf16 v[6:9], v[154:157], v[214:217], v[6:9]
	v_mfma_f32_16x16x32_bf16 v[2:5], v[172:175], v[214:217], v[2:5]
	v_mfma_f32_16x16x32_bf16 v[42:45], v[154:157], v[184:187], v[70:73]
	v_mfma_f32_16x16x32_bf16 v[46:49], v[172:175], v[184:187], v[66:69]
	v_mfma_f32_16x16x32_bf16 v[38:41], v[168:171], v[196:199], v[38:41]
	v_mfma_f32_16x16x32_bf16 v[34:37], v[180:183], v[196:199], v[34:37]
	v_mfma_f32_16x16x32_bf16 v[22:25], v[168:171], v[210:213], v[22:25]
	v_mfma_f32_16x16x32_bf16 v[18:21], v[180:183], v[210:213], v[18:21]
	v_mfma_f32_16x16x32_bf16 v[6:9], v[168:171], v[218:221], v[6:9]
	v_mfma_f32_16x16x32_bf16 v[2:5], v[180:183], v[218:221], v[2:5]
	v_mfma_f32_16x16x32_bf16 v[42:45], v[168:171], v[188:191], v[42:45]
	v_mfma_f32_16x16x32_bf16 v[46:49], v[180:183], v[188:191], v[46:49]
	s_barrier
	s_add_i32 s50, 0, 0x18000
	s_add_i32 s51, 0, 0x1c000
	ds_read_b128 v[50:53], v238
	ds_read_b128 v[54:57], v238 offset:1024
	ds_read_b128 v[66:69], v238 offset:2048
	ds_read_b128 v[70:73], v238 offset:3072
	ds_read_b128 v[154:157], v239
	ds_read_b128 v[168:171], v239 offset:1024
	ds_read_b128 v[172:175], v239 offset:2048
	ds_read_b128 v[180:183], v239 offset:3072
	s_add_u32 s22, s48, 0x160000
	s_addc_u32 s23, s49, 0
	s_mov_b32 m0, s52
	ds_read_b128 v[184:187], v178 offset:32768
	ds_read_b128 v[188:191], v178 offset:33792
	ds_read_b128 v[192:195], v178 offset:34816
	ds_read_b128 v[196:199], v178 offset:35840
	ds_read_b128 v[200:203], v178 offset:36864
	ds_read_b128 v[210:213], v178 offset:37888
	ds_read_b128 v[214:217], v178 offset:38912
	ds_read_b128 v[218:221], v178 offset:39936
	global_load_lds_dwordx4 v162, s[22:23]
	s_mov_b32 m0, s53
	s_nop 0
	global_load_lds_dwordx4 v160, s[22:23]
	s_waitcnt vmcnt(8) lgkmcnt(0)
	s_barrier
	v_mfma_f32_16x16x32_bf16 v[142:145], v[50:53], v[184:187], v[142:145]
	v_mfma_f32_16x16x32_bf16 v[138:141], v[66:69], v[184:187], v[138:141]
	v_mfma_f32_16x16x32_bf16 v[126:129], v[50:53], v[192:195], v[126:129]
	v_mfma_f32_16x16x32_bf16 v[122:125], v[66:69], v[192:195], v[122:125]
	v_mfma_f32_16x16x32_bf16 v[110:113], v[50:53], v[200:203], v[110:113]
	v_mfma_f32_16x16x32_bf16 v[106:109], v[66:69], v[200:203], v[106:109]
	v_mfma_f32_16x16x32_bf16 v[94:97], v[50:53], v[214:217], v[94:97]
	v_mfma_f32_16x16x32_bf16 v[90:93], v[66:69], v[214:217], v[90:93]
	v_mfma_f32_16x16x32_bf16 v[142:145], v[54:57], v[188:191], v[142:145]
	v_mfma_f32_16x16x32_bf16 v[138:141], v[70:73], v[188:191], v[138:141]
	v_mfma_f32_16x16x32_bf16 v[126:129], v[54:57], v[196:199], v[126:129]
	v_mfma_f32_16x16x32_bf16 v[122:125], v[70:73], v[196:199], v[122:125]
	v_mfma_f32_16x16x32_bf16 v[110:113], v[54:57], v[210:213], v[110:113]
	v_mfma_f32_16x16x32_bf16 v[106:109], v[70:73], v[210:213], v[106:109]
	v_mfma_f32_16x16x32_bf16 v[94:97], v[54:57], v[218:221], v[94:97]
	v_mfma_f32_16x16x32_bf16 v[90:93], v[70:73], v[218:221], v[90:93]
	v_mfma_f32_16x16x32_bf16 v[134:137], v[154:157], v[184:187], v[134:137]
	v_mfma_f32_16x16x32_bf16 v[130:133], v[172:175], v[184:187], v[130:133]
	v_mfma_f32_16x16x32_bf16 v[118:121], v[154:157], v[192:195], v[118:121]
	v_mfma_f32_16x16x32_bf16 v[114:117], v[172:175], v[192:195], v[114:117]
	v_mfma_f32_16x16x32_bf16 v[102:105], v[154:157], v[200:203], v[102:105]
	v_mfma_f32_16x16x32_bf16 v[98:101], v[172:175], v[200:203], v[98:101]
	v_mfma_f32_16x16x32_bf16 v[86:89], v[154:157], v[214:217], v[86:89]
	v_mfma_f32_16x16x32_bf16 v[82:85], v[172:175], v[214:217], v[82:85]
	v_mfma_f32_16x16x32_bf16 v[134:137], v[168:171], v[188:191], v[134:137]
	v_mfma_f32_16x16x32_bf16 v[130:133], v[180:183], v[188:191], v[130:133]
	v_mfma_f32_16x16x32_bf16 v[118:121], v[168:171], v[196:199], v[118:121]
	v_mfma_f32_16x16x32_bf16 v[114:117], v[180:183], v[196:199], v[114:117]
	v_mfma_f32_16x16x32_bf16 v[102:105], v[168:171], v[210:213], v[102:105]
	v_mfma_f32_16x16x32_bf16 v[98:101], v[180:183], v[210:213], v[98:101]
	v_mfma_f32_16x16x32_bf16 v[86:89], v[168:171], v[218:221], v[86:89]
	v_mfma_f32_16x16x32_bf16 v[82:85], v[180:183], v[218:221], v[82:85]
	s_barrier
	s_add_i32 s22, s50, s16
	v_lshl_add_u64 v[222:223], v[222:223], 0, s[34:35]
	s_mov_b32 m0, s22
	ds_read_b128 v[184:187], v178 offset:49152
	ds_read_b128 v[188:191], v178 offset:50176
	ds_read_b128 v[192:195], v178 offset:51200
	ds_read_b128 v[196:199], v178 offset:52224
	ds_read_b128 v[200:203], v178 offset:53248
	ds_read_b128 v[210:213], v178 offset:54272
	ds_read_b128 v[214:217], v178 offset:55296
	ds_read_b128 v[218:221], v178 offset:56320
	global_load_lds_dwordx4 v[222:223], off
	s_add_i32 m0, s22, 0x2000
	s_add_u32 s22, s46, 0x160080
	v_lshl_add_u64 v[222:223], v[224:225], 0, s[34:35]
	s_addc_u32 s23, s47, 0
	s_add_i32 s46, s51, s16
	global_load_lds_dwordx4 v[222:223], off
	s_mov_b32 m0, s46
	s_nop 0
	global_load_lds_dwordx4 v0, s[22:23]
	s_add_i32 m0, s46, 0x2000
	s_nop 0
	global_load_lds_dwordx4 v158, s[22:23]
	v_lshl_add_u64 v[222:223], v[226:227], 0, s[34:35]
	s_mov_b32 m0, s55
	s_nop 0
	global_load_lds_dwordx4 v[222:223], off
	v_lshl_add_u64 v[222:223], v[228:229], 0, s[34:35]
	s_mov_b32 m0, s56
	s_nop 0
	global_load_lds_dwordx4 v[222:223], off
	s_waitcnt vmcnt(8) lgkmcnt(0)
	s_barrier
	v_mfma_f32_16x16x32_bf16 v[78:81], v[50:53], v[184:187], v[78:81]
	v_mfma_f32_16x16x32_bf16 v[74:77], v[66:69], v[184:187], v[74:77]
	v_mfma_f32_16x16x32_bf16 v[62:65], v[50:53], v[192:195], v[62:65]
	v_mfma_f32_16x16x32_bf16 v[58:61], v[66:69], v[192:195], v[58:61]
	v_mfma_f32_16x16x32_bf16 v[30:33], v[50:53], v[200:203], v[30:33]
	v_mfma_f32_16x16x32_bf16 v[26:29], v[66:69], v[200:203], v[26:29]
	v_mfma_f32_16x16x32_bf16 v[14:17], v[50:53], v[214:217], v[14:17]
	v_mfma_f32_16x16x32_bf16 v[10:13], v[66:69], v[214:217], v[10:13]
	v_mfma_f32_16x16x32_bf16 v[78:81], v[54:57], v[188:191], v[78:81]
	v_mfma_f32_16x16x32_bf16 v[74:77], v[70:73], v[188:191], v[74:77]
	v_mfma_f32_16x16x32_bf16 v[62:65], v[54:57], v[196:199], v[62:65]
	v_mfma_f32_16x16x32_bf16 v[58:61], v[70:73], v[196:199], v[58:61]
	v_mfma_f32_16x16x32_bf16 v[30:33], v[54:57], v[210:213], v[30:33]
	v_mfma_f32_16x16x32_bf16 v[26:29], v[70:73], v[210:213], v[26:29]
	v_mfma_f32_16x16x32_bf16 v[14:17], v[54:57], v[218:221], v[14:17]
	v_mfma_f32_16x16x32_bf16 v[10:13], v[70:73], v[218:221], v[10:13]
	v_mfma_f32_16x16x32_bf16 v[42:45], v[154:157], v[184:187], v[42:45]
	v_mfma_f32_16x16x32_bf16 v[70:73], v[168:171], v[188:191], v[42:45]
	v_mfma_f32_16x16x32_bf16 v[42:45], v[172:175], v[184:187], v[46:49]
	v_mfma_f32_16x16x32_bf16 v[38:41], v[154:157], v[192:195], v[38:41]
	v_mfma_f32_16x16x32_bf16 v[34:37], v[172:175], v[192:195], v[34:37]
	v_mfma_f32_16x16x32_bf16 v[22:25], v[154:157], v[200:203], v[22:25]
	v_mfma_f32_16x16x32_bf16 v[18:21], v[172:175], v[200:203], v[18:21]
	v_mfma_f32_16x16x32_bf16 v[6:9], v[154:157], v[214:217], v[6:9]
	v_mfma_f32_16x16x32_bf16 v[2:5], v[172:175], v[214:217], v[2:5]
	v_mfma_f32_16x16x32_bf16 v[66:69], v[180:183], v[188:191], v[42:45]
	v_mfma_f32_16x16x32_bf16 v[38:41], v[168:171], v[196:199], v[38:41]
	v_mfma_f32_16x16x32_bf16 v[34:37], v[180:183], v[196:199], v[34:37]
	v_mfma_f32_16x16x32_bf16 v[22:25], v[168:171], v[210:213], v[22:25]
	v_mfma_f32_16x16x32_bf16 v[18:21], v[180:183], v[210:213], v[18:21]
	v_mfma_f32_16x16x32_bf16 v[6:9], v[168:171], v[218:221], v[6:9]
	v_mfma_f32_16x16x32_bf16 v[2:5], v[180:183], v[218:221], v[2:5]
	s_barrier
	s_add_i32 s25, s25, 2
	s_add_u32 s18, s18, 0x100
	s_addc_u32 s19, s19, 0
	s_cmpk_gt_u32 s25, 0x55
	s_mov_b64 s[22:23], s[42:43]
	s_cbranch_scc0 .LBB0_728
	s_setprio 0
	s_and_b64 vcc, exec, s[12:13]
	s_cbranch_vccz .LBB0_731
	s_barrier
